# stack D + half of each XCD's workgroups start the two swiglu GEMM phases 10us late (de-synchronise epilogue bursts)
# baseline (speedup 1.0000x reference)
.LBB0_614:
	s_bitcmp1_b32 s2, 3
	s_cbranch_scc0 .Lstg7_skip
	s_memrealtime s[100:101]
	s_waitcnt lgkmcnt(0)
	s_add_u32 s100, s100, 1000
	s_addc_u32 s101, s101, 0
.Lstg7_spin:
	s_memrealtime s[98:99]
	s_waitcnt lgkmcnt(0)
	s_sub_u32 s98, s98, s100
	s_subb_u32 s99, s99, s101
	s_cmp_lt_i32 s99, 0
	s_cbranch_scc1 .Lstg7_spin
